# sample-uv task epilogue: batch the 8 serialized z ushort loads and the silu math
# baseline (speedup 1.0000x reference)
.Lsg2_tail:
	s_waitcnt vmcnt(21)
	v_mfma_f32_16x16x32_bf16 v[6:9], v[20:23], v[24:27], v[6:9]
	v_mfma_f32_16x16x32_bf16 v[2:5], v[20:23], v[32:35], v[2:5]
	s_waitcnt vmcnt(18)
	v_mfma_f32_16x16x32_bf16 v[6:9], v[96:99], v[100:103], v[6:9]
	v_mfma_f32_16x16x32_bf16 v[2:5], v[96:99], v[104:107], v[2:5]
	s_waitcnt vmcnt(15)
	v_mfma_f32_16x16x32_bf16 v[6:9], v[108:111], v[112:115], v[6:9]
	v_mfma_f32_16x16x32_bf16 v[2:5], v[108:111], v[116:119], v[2:5]
	s_waitcnt vmcnt(12)
	v_mfma_f32_16x16x32_bf16 v[6:9], v[120:123], v[124:127], v[6:9]
	v_mfma_f32_16x16x32_bf16 v[2:5], v[120:123], v[128:131], v[2:5]
	s_waitcnt vmcnt(9)
	v_mfma_f32_16x16x32_bf16 v[6:9], v[132:135], v[136:139], v[6:9]
	v_mfma_f32_16x16x32_bf16 v[2:5], v[132:135], v[140:143], v[2:5]
	s_waitcnt vmcnt(6)
	v_mfma_f32_16x16x32_bf16 v[6:9], v[144:147], v[148:151], v[6:9]
	v_mfma_f32_16x16x32_bf16 v[2:5], v[144:147], v[152:155], v[2:5]
	s_waitcnt vmcnt(3)
	v_mfma_f32_16x16x32_bf16 v[6:9], v[156:159], v[160:163], v[6:9]
	v_mfma_f32_16x16x32_bf16 v[2:5], v[156:159], v[164:167], v[2:5]
	s_waitcnt vmcnt(0)
	v_mfma_f32_16x16x32_bf16 v[6:9], v[172:175], v[176:179], v[6:9]
	v_mfma_f32_16x16x32_bf16 v[2:5], v[172:175], v[180:183], v[2:5]
	s_add_i32 s0, s62, 0xfffffe7e
	s_lshl_b32 s17, s0, 4
	s_and_b32 s17, s17, 0x70
	v_lshrrev_b32_e32 v0, 2, v30
	v_and_or_b32 v0, v0, 12, s17
	v_or_b32_e32 v0, 0x4000, v0
	v_mul_u32_u24_e32 v0, 0x1c00, v0
	s_lshl_b32 s0, s0, 5
	v_lshlrev_b32_e32 v0, 1, v0
	s_and_b32 s0, s0, 0xffffff00
	v_lshl_add_u64 v[12:13], s[4:5], 0, v[0:1]
	v_ashrrev_i32_e32 v11, 31, v10
	v_lshl_add_u64 v[12:13], s[0:1], 1, v[12:13]
	v_lshl_add_u64 v[10:11], v[10:11], 1, v[12:13]
	v_lshlrev_b32_e32 v0, 1, v18
	v_lshl_add_u64 v[10:11], v[10:11], 0, v[0:1]
	s_mov_b64 s[18:19], 0x3c00
	v_lshl_add_u64 v[116:117], v[10:11], 0, s[18:19]
	s_mov_b64 s[18:19], 0x7400
	v_lshl_add_u64 v[118:119], v[10:11], 0, s[18:19]
	s_mov_b64 s[18:19], 0xac00
	v_lshl_add_u64 v[120:121], v[10:11], 0, s[18:19]
	global_load_ushort v108, v[10:11], off offset:1024
	global_load_ushort v109, v[10:11], off offset:1056
	global_load_ushort v110, v[116:117], off
	global_load_ushort v111, v[116:117], off offset:32
	global_load_ushort v112, v[118:119], off
	global_load_ushort v113, v[118:119], off offset:32
	global_load_ushort v114, v[120:121], off
	global_load_ushort v115, v[120:121], off offset:32
	s_waitcnt vmcnt(0)
	v_lshlrev_b32_e32 v108, 16, v108
	v_lshlrev_b32_e32 v109, 16, v109
	v_lshlrev_b32_e32 v110, 16, v110
	v_lshlrev_b32_e32 v111, 16, v111
	v_lshlrev_b32_e32 v112, 16, v112
	v_lshlrev_b32_e32 v113, 16, v113
	v_lshlrev_b32_e32 v114, 16, v114
	v_lshlrev_b32_e32 v115, 16, v115
	v_mul_f32_e32 v122, 0xbfb8aa3b, v108
	v_mul_f32_e32 v123, 0xbfb8aa3b, v109
	v_mul_f32_e32 v124, 0xbfb8aa3b, v110
	v_mul_f32_e32 v125, 0xbfb8aa3b, v111
	v_mul_f32_e32 v126, 0xbfb8aa3b, v112
	v_mul_f32_e32 v127, 0xbfb8aa3b, v113
	v_mul_f32_e32 v128, 0xbfb8aa3b, v114
	v_mul_f32_e32 v129, 0xbfb8aa3b, v115
	v_exp_f32_e32 v122, v122
	v_exp_f32_e32 v123, v123
	v_exp_f32_e32 v124, v124
	v_exp_f32_e32 v125, v125
	v_exp_f32_e32 v126, v126
	v_exp_f32_e32 v127, v127
	v_exp_f32_e32 v128, v128
	v_exp_f32_e32 v129, v129
	v_add_f32_e32 v122, 1.0, v122
	v_add_f32_e32 v123, 1.0, v123
	v_add_f32_e32 v124, 1.0, v124
	v_add_f32_e32 v125, 1.0, v125
	v_add_f32_e32 v126, 1.0, v126
	v_add_f32_e32 v127, 1.0, v127
	v_add_f32_e32 v128, 1.0, v128
	v_add_f32_e32 v129, 1.0, v129
	v_rcp_f32_e32 v122, v122
	v_rcp_f32_e32 v123, v123
	v_rcp_f32_e32 v124, v124
	v_rcp_f32_e32 v125, v125
	v_rcp_f32_e32 v126, v126
	v_rcp_f32_e32 v127, v127
	v_rcp_f32_e32 v128, v128
	v_rcp_f32_e32 v129, v129
	v_mul_f32_e32 v108, v108, v122
	v_mul_f32_e32 v109, v109, v123
	v_mul_f32_e32 v110, v110, v124
	v_mul_f32_e32 v111, v111, v125
	v_mul_f32_e32 v112, v112, v126
	v_mul_f32_e32 v113, v113, v127
	v_mul_f32_e32 v114, v114, v128
	v_mul_f32_e32 v115, v115, v129
	v_mul_f32_e32 v108, v6, v108
	v_mul_f32_e32 v109, v2, v109
	v_mul_f32_e32 v110, v7, v110
	v_mul_f32_e32 v111, v3, v111
	v_mul_f32_e32 v112, v8, v112
	v_mul_f32_e32 v113, v4, v113
	v_mul_f32_e32 v114, v9, v114
	v_mul_f32_e32 v115, v5, v115
	v_cvt_pk_bf16_f32 v108, v108, v108
	v_cvt_pk_bf16_f32 v109, v109, v109
	v_cvt_pk_bf16_f32 v110, v110, v110
	v_cvt_pk_bf16_f32 v111, v111, v111
	v_cvt_pk_bf16_f32 v112, v112, v112
	v_cvt_pk_bf16_f32 v113, v113, v113
	v_cvt_pk_bf16_f32 v114, v114, v114
	v_cvt_pk_bf16_f32 v115, v115, v115
	global_store_short v[10:11], v108, off offset:2048
	global_store_short v[10:11], v109, off offset:2080
	global_store_short v[116:117], v110, off offset:1024
	global_store_short v[116:117], v111, off offset:1056
	global_store_short v[118:119], v112, off offset:1024
	global_store_short v[118:119], v113, off offset:1056
	global_store_short v[120:121], v114, off offset:1024
	global_store_short v[120:121], v115, off offset:1056
